# V^T image transposed through a wave-private LDS tile and stored with dwordx4 instead of 64 short stores per lane
# speedup vs baseline: 1.0148x; 1.0001x over previous
; __device__ __forceinline__ int keypos(int key) { return (key & ~12) | ((key & 4) << 1) | ((key & 8) >> 1); }
; __device__ __forceinline__ void s2_vt_images(Frame& F) {
;     ...
;     for (int it = F.gw; it < 2 * PB * 4 * 64; it += F.ngw) {
;         const int which = it >> 9, b = (it >> 8) & 1, kvh = (it >> 6) & 3, blk = it & 63;
;         const bf16_t* src = P + (size_t)(b * SEQ + blk * 64 + F.lane) * NPROJ + (which ? C_WV : C_SV) + kvh * 64;
;         const int pos = keypos(F.lane);
;         bf16_t* img = (bf16_t*)(F.ws + (which ? WS_VTWIN : WS_VTSEL)) + (size_t)((b * 4 + kvh) * 64 + blk) * 4096 + (pos >> 3) * 512 + (pos & 7);
;         u32x4 v[8];
; #pragma unroll
;         for (int j = 0; j < 8; ++j) v[j] = *(const u32x4*)(src + 8 * j);
; #pragma unroll
;         for (int j = 0; j < 8; ++j) {
;             img[(8 * j + 0) * 8] = (bf16_t)(v[j].x & 0xffffu); img[(8 * j + 1) * 8] = (bf16_t)(v[j].x >> 16);
;             img[(8 * j + 2) * 8] = (bf16_t)(v[j].y & 0xffffu); img[(8 * j + 3) * 8] = (bf16_t)(v[j].y >> 16);
;             img[(8 * j + 4) * 8] = (bf16_t)(v[j].z & 0xffffu); img[(8 * j + 5) * 8] = (bf16_t)(v[j].z >> 16);
;             img[(8 * j + 6) * 8] = (bf16_t)(v[j].w & 0xffffu); img[(8 * j + 7) * 8] = (bf16_t)(v[j].w >> 16); }
;     }
.LBB0_567:
	s_bfe_u32 s14, s8, 0x10008
	s_and_b32 s23, s8, 63
	s_lshl_b32 s4, s14, 12
	s_lshl_b32 s16, s23, 6
	s_and_b32 s22, s8, 0xc0
	s_or_b32 s4, s4, s16
	v_or_b32_e32 v3, s4, v6
	s_lshl_b32 s16, s22, 1
	v_mul_u32_u24_e32 v98, 0x6e00, v3
	s_cmpk_lt_u32 s8, 0x200
	s_movk_i32 s4, 0x2200
	v_lshl_add_u64 v[8:9], s[44:45], 0, v[98:99]
	s_cselect_b32 s4, 0x1e00, s4
	v_lshl_add_u64 v[8:9], v[8:9], 0, s[4:5]
	s_cselect_b32 s4, s3, 0x20a00000
	s_mov_b32 s17, s5
	s_add_u32 s4, s40, s4
	v_lshl_add_u64 v[36:37], v[8:9], 0, s[16:17]
	s_addc_u32 s17, s41, 0
	s_lshl_b32 s14, s14, 8
	s_or_b32 s14, s14, s22
	s_or_b32 s14, s14, s23
	s_lshl_b32 s14, s14, 13
	s_add_u32 s16, s4, s14
	s_addc_u32 s17, s17, 0
	v_mov_b32_e32 v3, v99
	v_lshl_add_u64 v[8:9], s[16:17], 0, v[2:3]
	v_mov_b32_e32 v5, v99
	v_lshl_add_u64 v[40:41], v[8:9], 0, v[4:5]
	global_load_dwordx4 v[8:11], v[36:37], off
	global_load_dwordx4 v[12:15], v[36:37], off offset:16
	global_load_dwordx4 v[16:19], v[36:37], off offset:32
	global_load_dwordx4 v[20:23], v[36:37], off offset:48
	global_load_dwordx4 v[24:27], v[36:37], off offset:64
	global_load_dwordx4 v[28:31], v[36:37], off offset:80
	global_load_dwordx4 v[32:35], v[36:37], off offset:96
	s_nop 0
	global_load_dwordx4 v[36:39], v[36:37], off offset:112
	s_add_i32 s8, s8, s88
	s_cmpk_lt_i32 s8, 0x400
	s_waitcnt vmcnt(0)
	v_lshrrev_b32_e32 v42, 6, v0
	v_lshlrev_b32_e32 v42, 13, v42
	v_add3_u32 v43, v42, v2, v4
	v_lshl_add_u32 v42, v6, 4, v42
	v_lshlrev_b32_e32 v76, 4, v6
	v_add_u32_e32 v77, 0x1000, v76
	ds_write_b16 v43, v8
	ds_write_b16_d16_hi v43, v8 offset:16
	ds_write_b16 v43, v9 offset:32
	ds_write_b16_d16_hi v43, v9 offset:48
	ds_write_b16 v43, v10 offset:64
	ds_write_b16_d16_hi v43, v10 offset:80
	ds_write_b16 v43, v11 offset:96
	ds_write_b16_d16_hi v43, v11 offset:112
	ds_write_b16 v43, v12 offset:128
	ds_write_b16_d16_hi v43, v12 offset:144
	ds_write_b16 v43, v13 offset:160
	ds_write_b16_d16_hi v43, v13 offset:176
	ds_write_b16 v43, v14 offset:192
	ds_write_b16_d16_hi v43, v14 offset:208
	ds_write_b16 v43, v15 offset:224
	ds_write_b16_d16_hi v43, v15 offset:240
	ds_write_b16 v43, v16 offset:256
	ds_write_b16_d16_hi v43, v16 offset:272
	ds_write_b16 v43, v17 offset:288
	ds_write_b16_d16_hi v43, v17 offset:304
	ds_write_b16 v43, v18 offset:320
	ds_write_b16_d16_hi v43, v18 offset:336
	ds_write_b16 v43, v19 offset:352
	ds_write_b16_d16_hi v43, v19 offset:368
	ds_write_b16 v43, v20 offset:384
	ds_write_b16_d16_hi v43, v20 offset:400
	ds_write_b16 v43, v21 offset:416
	ds_write_b16_d16_hi v43, v21 offset:432
	ds_write_b16 v43, v22 offset:448
	ds_write_b16_d16_hi v43, v22 offset:464
	ds_write_b16 v43, v23 offset:480
	ds_write_b16_d16_hi v43, v23 offset:496
	ds_write_b16 v43, v24 offset:512
	ds_write_b16_d16_hi v43, v24 offset:528
	ds_write_b16 v43, v25 offset:544
	ds_write_b16_d16_hi v43, v25 offset:560
	ds_write_b16 v43, v26 offset:576
	ds_write_b16_d16_hi v43, v26 offset:592
	ds_write_b16 v43, v27 offset:608
	ds_write_b16_d16_hi v43, v27 offset:624
	ds_write_b16 v43, v28 offset:640
	ds_write_b16_d16_hi v43, v28 offset:656
	ds_write_b16 v43, v29 offset:672
	ds_write_b16_d16_hi v43, v29 offset:688
	ds_write_b16 v43, v30 offset:704
	ds_write_b16_d16_hi v43, v30 offset:720
	ds_write_b16 v43, v31 offset:736
	ds_write_b16_d16_hi v43, v31 offset:752
	ds_write_b16 v43, v32 offset:768
	ds_write_b16_d16_hi v43, v32 offset:784
	ds_write_b16 v43, v33 offset:800
	ds_write_b16_d16_hi v43, v33 offset:816
	ds_write_b16 v43, v34 offset:832
	ds_write_b16_d16_hi v43, v34 offset:848
	ds_write_b16 v43, v35 offset:864
	ds_write_b16_d16_hi v43, v35 offset:880
	ds_write_b16 v43, v36 offset:896
	ds_write_b16_d16_hi v43, v36 offset:912
	ds_write_b16 v43, v37 offset:928
	ds_write_b16_d16_hi v43, v37 offset:944
	ds_write_b16 v43, v38 offset:960
	ds_write_b16_d16_hi v43, v38 offset:976
	ds_write_b16 v43, v39 offset:992
	ds_write_b16_d16_hi v43, v39 offset:1008
	s_waitcnt lgkmcnt(0)
	ds_read_b128 v[44:47], v42
	ds_read_b128 v[48:51], v42 offset:1024
	ds_read_b128 v[52:55], v42 offset:2048
	ds_read_b128 v[56:59], v42 offset:3072
	ds_read_b128 v[60:63], v42 offset:4096
	ds_read_b128 v[64:67], v42 offset:5120
	ds_read_b128 v[68:71], v42 offset:6144
	ds_read_b128 v[72:75], v42 offset:7168
	s_waitcnt lgkmcnt(7)
	global_store_dwordx4 v76, v[44:47], s[16:17]
	s_waitcnt lgkmcnt(6)
	global_store_dwordx4 v76, v[48:51], s[16:17] offset:1024
	s_waitcnt lgkmcnt(5)
	global_store_dwordx4 v76, v[52:55], s[16:17] offset:2048
	s_waitcnt lgkmcnt(4)
	global_store_dwordx4 v76, v[56:59], s[16:17] offset:3072
	s_waitcnt lgkmcnt(3)
	global_store_dwordx4 v77, v[60:63], s[16:17]
	s_waitcnt lgkmcnt(2)
	global_store_dwordx4 v77, v[64:67], s[16:17] offset:1024
	s_waitcnt lgkmcnt(1)
	global_store_dwordx4 v77, v[68:71], s[16:17] offset:2048
	s_waitcnt lgkmcnt(0)
	global_store_dwordx4 v77, v[72:75], s[16:17] offset:3072
	s_cbranch_scc1 .LBB0_567
